# v106 plus s_setprio 1 for the wr==0 wave half across P1's store epilogue (post-barrier segment), reset to 0 at the epilogue end
# speedup vs baseline: 1.0138x; 1.0138x over previous
.LBB0_75:
	ds_read_b128 v[144:147], v151
	ds_read_b128 v[154:157], v151 offset:1024
	ds_read_b128 v[162:165], v151 offset:2048
	ds_read_b128 v[166:169], v151 offset:3072
	ds_read_b128 v[170:173], v152
	ds_read_b128 v[174:177], v152 offset:1024
	ds_read_b128 v[182:185], v152 offset:2048
	ds_read_b128 v[186:189], v152 offset:3072
	s_add_u32 s50, s40, 0xfffc0080
	s_addc_u32 s51, s41, -1
	s_cmp_eq_u32 s83, 12
	s_cselect_b32 s71, s21, s51
	s_cselect_b32 s70, s20, s50
	s_cselect_b32 s51, s23, s19
	s_cselect_b32 s50, s22, s17
	v_lshl_add_u64 v[158:159], s[40:41], 0, v[136:137]
	s_add_i32 m0, s25, 0xc000
	ds_read_b128 v[190:193], v153
	ds_read_b128 v[194:197], v153 offset:1024
	ds_read_b128 v[198:201], v153 offset:2048
	ds_read_b128 v[202:205], v153 offset:3072
	ds_read_b128 v[206:209], v153 offset:4096
	ds_read_b128 v[210:213], v153 offset:5120
	ds_read_b128 v[214:217], v153 offset:6144
	ds_read_b128 v[218:221], v153 offset:7168
	global_load_lds_dwordx4 v[158:159], off
	v_lshl_add_u64 v[158:159], s[40:41], 0, v[138:139]
	s_add_i32 m0, s25, 0xe000
	s_nop 0
	global_load_lds_dwordx4 v[158:159], off
	s_waitcnt vmcnt(8)
	s_waitcnt lgkmcnt(0)
	s_barrier
	s_setprio 1
	s_waitcnt lgkmcnt(0)
	v_mfma_f32_16x16x32_bf16 v[124:127], v[144:147], v[190:193], v[124:127]
	v_mfma_f32_16x16x32_bf16 v[120:123], v[162:165], v[190:193], v[120:123]
	v_mfma_f32_16x16x32_bf16 v[116:119], v[144:147], v[198:201], v[116:119]
	v_mfma_f32_16x16x32_bf16 v[108:111], v[162:165], v[198:201], v[108:111]
	v_mfma_f32_16x16x32_bf16 v[100:103], v[144:147], v[206:209], v[100:103]
	v_mfma_f32_16x16x32_bf16 v[92:95], v[162:165], v[206:209], v[92:95]
	v_mfma_f32_16x16x32_bf16 v[84:87], v[144:147], v[214:217], v[84:87]
	v_mfma_f32_16x16x32_bf16 v[76:79], v[162:165], v[214:217], v[76:79]
	v_mfma_f32_16x16x32_bf16 v[124:127], v[154:157], v[194:197], v[124:127]
	v_mfma_f32_16x16x32_bf16 v[120:123], v[166:169], v[194:197], v[120:123]
	v_mfma_f32_16x16x32_bf16 v[116:119], v[154:157], v[202:205], v[116:119]
	v_mfma_f32_16x16x32_bf16 v[108:111], v[166:169], v[202:205], v[108:111]
	v_mfma_f32_16x16x32_bf16 v[100:103], v[154:157], v[210:213], v[100:103]
	v_mfma_f32_16x16x32_bf16 v[92:95], v[166:169], v[210:213], v[92:95]
	v_mfma_f32_16x16x32_bf16 v[84:87], v[154:157], v[218:221], v[84:87]
	v_mfma_f32_16x16x32_bf16 v[76:79], v[166:169], v[218:221], v[76:79]
	s_setprio 0
	s_setprio 1
	v_mfma_f32_16x16x32_bf16 v[112:115], v[170:173], v[190:193], v[112:115]
	v_mfma_f32_16x16x32_bf16 v[104:107], v[182:185], v[190:193], v[104:107]
	v_mfma_f32_16x16x32_bf16 v[96:99], v[170:173], v[198:201], v[96:99]
	v_mfma_f32_16x16x32_bf16 v[88:91], v[182:185], v[198:201], v[88:91]
	v_mfma_f32_16x16x32_bf16 v[80:83], v[170:173], v[206:209], v[80:83]
	v_mfma_f32_16x16x32_bf16 v[72:75], v[182:185], v[206:209], v[72:75]
	v_mfma_f32_16x16x32_bf16 v[68:71], v[170:173], v[214:217], v[68:71]
	v_mfma_f32_16x16x32_bf16 v[64:67], v[182:185], v[214:217], v[64:67]
	v_mfma_f32_16x16x32_bf16 v[112:115], v[174:177], v[194:197], v[112:115]
	v_mfma_f32_16x16x32_bf16 v[104:107], v[186:189], v[194:197], v[104:107]
	v_mfma_f32_16x16x32_bf16 v[96:99], v[174:177], v[202:205], v[96:99]
	v_mfma_f32_16x16x32_bf16 v[88:91], v[186:189], v[202:205], v[88:91]
	v_mfma_f32_16x16x32_bf16 v[80:83], v[174:177], v[210:213], v[80:83]
	v_mfma_f32_16x16x32_bf16 v[72:75], v[186:189], v[210:213], v[72:75]
	v_mfma_f32_16x16x32_bf16 v[68:71], v[174:177], v[218:221], v[68:71]
	v_mfma_f32_16x16x32_bf16 v[64:67], v[186:189], v[218:221], v[64:67]
	s_setprio 0
	s_barrier
	s_add_i32 s84, s79, s3
	v_lshl_add_u64 v[158:159], s[50:51], 0, v[132:133]
	s_mov_b32 m0, s84
	ds_read_b128 v[190:193], v153 offset:16384
	ds_read_b128 v[194:197], v153 offset:17408
	ds_read_b128 v[198:201], v153 offset:18432
	ds_read_b128 v[202:205], v153 offset:19456
	ds_read_b128 v[206:209], v153 offset:20480
	ds_read_b128 v[210:213], v153 offset:21504
	ds_read_b128 v[214:217], v153 offset:22528
	ds_read_b128 v[218:221], v153 offset:23552
	global_load_lds_dwordx4 v[158:159], off
	s_add_i32 m0, s84, 0x2000
	s_add_u32 s84, s50, 0x40000
	v_lshl_add_u64 v[178:179], s[50:51], 0, v[128:129]
	s_addc_u32 s85, s51, 0
	s_add_i32 s86, s80, s3
	global_load_lds_dwordx4 v[178:179], off
	v_lshl_add_u64 v[222:223], s[84:85], 0, v[132:133]
	s_mov_b32 m0, s86
	v_lshl_add_u64 v[224:225], s[70:71], 0, v[130:131]
	global_load_lds_dwordx4 v[222:223], off
	v_lshl_add_u64 v[222:223], s[84:85], 0, v[128:129]
	s_add_i32 m0, s86, 0x2000
	s_nop 0
	global_load_lds_dwordx4 v[222:223], off
	v_lshl_add_u64 v[222:223], s[70:71], 0, v[134:135]
	s_mov_b32 m0, s25
	s_nop 0
	global_load_lds_dwordx4 v[222:223], off
	s_mov_b32 m0, s72
	s_nop 0
	global_load_lds_dwordx4 v[224:225], off
	s_waitcnt vmcnt(8)
	s_waitcnt lgkmcnt(0)
	s_barrier
	s_setprio 1
	s_waitcnt lgkmcnt(0)
	v_mfma_f32_16x16x32_bf16 v[60:63], v[144:147], v[190:193], v[60:63]
	v_mfma_f32_16x16x32_bf16 v[56:59], v[162:165], v[190:193], v[56:59]
	v_mfma_f32_16x16x32_bf16 v[52:55], v[144:147], v[198:201], v[52:55]
	v_mfma_f32_16x16x32_bf16 v[44:47], v[162:165], v[198:201], v[44:47]
	v_mfma_f32_16x16x32_bf16 v[36:39], v[144:147], v[206:209], v[36:39]
	v_mfma_f32_16x16x32_bf16 v[28:31], v[162:165], v[206:209], v[28:31]
	v_mfma_f32_16x16x32_bf16 v[20:23], v[144:147], v[214:217], v[20:23]
	v_mfma_f32_16x16x32_bf16 v[12:15], v[162:165], v[214:217], v[12:15]
	v_mfma_f32_16x16x32_bf16 v[60:63], v[154:157], v[194:197], v[60:63]
	v_mfma_f32_16x16x32_bf16 v[56:59], v[166:169], v[194:197], v[56:59]
	v_mfma_f32_16x16x32_bf16 v[52:55], v[154:157], v[202:205], v[52:55]
	v_mfma_f32_16x16x32_bf16 v[44:47], v[166:169], v[202:205], v[44:47]
	v_mfma_f32_16x16x32_bf16 v[36:39], v[154:157], v[210:213], v[36:39]
	v_mfma_f32_16x16x32_bf16 v[28:31], v[166:169], v[210:213], v[28:31]
	v_mfma_f32_16x16x32_bf16 v[20:23], v[154:157], v[218:221], v[20:23]
	v_mfma_f32_16x16x32_bf16 v[12:15], v[166:169], v[218:221], v[12:15]
	s_setprio 0
	s_setprio 1
	v_mfma_f32_16x16x32_bf16 v[48:51], v[170:173], v[190:193], v[48:51]
	v_mfma_f32_16x16x32_bf16 v[40:43], v[182:185], v[190:193], v[40:43]
	v_mfma_f32_16x16x32_bf16 v[32:35], v[170:173], v[198:201], v[32:35]
	v_mfma_f32_16x16x32_bf16 v[24:27], v[182:185], v[198:201], v[24:27]
	v_mfma_f32_16x16x32_bf16 v[16:19], v[170:173], v[206:209], v[16:19]
	v_mfma_f32_16x16x32_bf16 v[8:11], v[182:185], v[206:209], v[8:11]
	v_mfma_f32_16x16x32_bf16 v[4:7], v[170:173], v[214:217], v[4:7]
	v_mfma_f32_16x16x32_bf16 v[0:3], v[182:185], v[214:217], v[0:3]
	v_mfma_f32_16x16x32_bf16 v[48:51], v[174:177], v[194:197], v[48:51]
	v_mfma_f32_16x16x32_bf16 v[40:43], v[186:189], v[194:197], v[40:43]
	v_mfma_f32_16x16x32_bf16 v[32:35], v[174:177], v[202:205], v[32:35]
	v_mfma_f32_16x16x32_bf16 v[24:27], v[186:189], v[202:205], v[24:27]
	v_mfma_f32_16x16x32_bf16 v[16:19], v[174:177], v[210:213], v[16:19]
	v_mfma_f32_16x16x32_bf16 v[8:11], v[186:189], v[210:213], v[8:11]
	v_mfma_f32_16x16x32_bf16 v[4:7], v[174:177], v[218:221], v[4:7]
	v_mfma_f32_16x16x32_bf16 v[0:3], v[186:189], v[218:221], v[0:3]
	s_setprio 0
	s_barrier
	s_add_i32 s84, 0, 0x18000
	v_add_u32_e32 v160, s84, v149
	s_add_i32 s85, 0, 0x1c000
	ds_read_b128 v[144:147], v160
	ds_read_b128 v[154:157], v160 offset:1024
	ds_read_b128 v[162:165], v160 offset:2048
	ds_read_b128 v[166:169], v160 offset:3072
	v_add_u32_e32 v160, s85, v149
	ds_read_b128 v[170:173], v160
	ds_read_b128 v[174:177], v160 offset:1024
	ds_read_b128 v[182:185], v160 offset:2048
	ds_read_b128 v[186:189], v160 offset:3072
	s_add_u32 s70, s70, 0x40000
	s_addc_u32 s71, s71, 0
	s_mov_b32 m0, s73
	v_lshl_add_u64 v[226:227], s[70:71], 0, v[134:135]
	ds_read_b128 v[190:193], v153 offset:32768
	ds_read_b128 v[194:197], v153 offset:33792
	ds_read_b128 v[198:201], v153 offset:34816
	ds_read_b128 v[202:205], v153 offset:35840
	ds_read_b128 v[206:209], v153 offset:36864
	ds_read_b128 v[210:213], v153 offset:37888
	ds_read_b128 v[214:217], v153 offset:38912
	ds_read_b128 v[218:221], v153 offset:39936
	global_load_lds_dwordx4 v[226:227], off
	v_lshl_add_u64 v[226:227], s[70:71], 0, v[130:131]
	s_mov_b32 m0, s74
	s_nop 0
	global_load_lds_dwordx4 v[226:227], off
	s_waitcnt vmcnt(8)
	s_waitcnt lgkmcnt(0)
	s_barrier
	s_setprio 1
	s_waitcnt lgkmcnt(0)
	v_mfma_f32_16x16x32_bf16 v[124:127], v[144:147], v[190:193], v[124:127]
	v_mfma_f32_16x16x32_bf16 v[120:123], v[162:165], v[190:193], v[120:123]
	v_mfma_f32_16x16x32_bf16 v[116:119], v[144:147], v[198:201], v[116:119]
	v_mfma_f32_16x16x32_bf16 v[108:111], v[162:165], v[198:201], v[108:111]
	v_mfma_f32_16x16x32_bf16 v[100:103], v[144:147], v[206:209], v[100:103]
	v_mfma_f32_16x16x32_bf16 v[92:95], v[162:165], v[206:209], v[92:95]
	v_mfma_f32_16x16x32_bf16 v[84:87], v[144:147], v[214:217], v[84:87]
	v_mfma_f32_16x16x32_bf16 v[76:79], v[162:165], v[214:217], v[76:79]
	v_mfma_f32_16x16x32_bf16 v[124:127], v[154:157], v[194:197], v[124:127]
	v_mfma_f32_16x16x32_bf16 v[120:123], v[166:169], v[194:197], v[120:123]
	v_mfma_f32_16x16x32_bf16 v[116:119], v[154:157], v[202:205], v[116:119]
	v_mfma_f32_16x16x32_bf16 v[108:111], v[166:169], v[202:205], v[108:111]
	v_mfma_f32_16x16x32_bf16 v[100:103], v[154:157], v[210:213], v[100:103]
	v_mfma_f32_16x16x32_bf16 v[92:95], v[166:169], v[210:213], v[92:95]
	v_mfma_f32_16x16x32_bf16 v[84:87], v[154:157], v[218:221], v[84:87]
	v_mfma_f32_16x16x32_bf16 v[76:79], v[166:169], v[218:221], v[76:79]
	s_setprio 0
	s_setprio 1
	v_mfma_f32_16x16x32_bf16 v[112:115], v[170:173], v[190:193], v[112:115]
	v_mfma_f32_16x16x32_bf16 v[104:107], v[182:185], v[190:193], v[104:107]
	v_mfma_f32_16x16x32_bf16 v[96:99], v[170:173], v[198:201], v[96:99]
	v_mfma_f32_16x16x32_bf16 v[88:91], v[182:185], v[198:201], v[88:91]
	v_mfma_f32_16x16x32_bf16 v[80:83], v[170:173], v[206:209], v[80:83]
	v_mfma_f32_16x16x32_bf16 v[72:75], v[182:185], v[206:209], v[72:75]
	v_mfma_f32_16x16x32_bf16 v[68:71], v[170:173], v[214:217], v[68:71]
	v_mfma_f32_16x16x32_bf16 v[64:67], v[182:185], v[214:217], v[64:67]
	v_mfma_f32_16x16x32_bf16 v[112:115], v[174:177], v[194:197], v[112:115]
	v_mfma_f32_16x16x32_bf16 v[104:107], v[186:189], v[194:197], v[104:107]
	v_mfma_f32_16x16x32_bf16 v[96:99], v[174:177], v[202:205], v[96:99]
	v_mfma_f32_16x16x32_bf16 v[88:91], v[186:189], v[202:205], v[88:91]
	v_mfma_f32_16x16x32_bf16 v[80:83], v[174:177], v[210:213], v[80:83]
	v_mfma_f32_16x16x32_bf16 v[72:75], v[186:189], v[210:213], v[72:75]
	v_mfma_f32_16x16x32_bf16 v[68:71], v[174:177], v[218:221], v[68:71]
	v_mfma_f32_16x16x32_bf16 v[64:67], v[186:189], v[218:221], v[64:67]
	s_setprio 0
	s_barrier
	s_add_i32 s70, s84, s3
	v_lshl_add_u64 v[158:159], v[158:159], 0, s[8:9]
	s_mov_b32 m0, s70
	ds_read_b128 v[190:193], v153 offset:49152
	ds_read_b128 v[194:197], v153 offset:50176
	ds_read_b128 v[198:201], v153 offset:51200
	ds_read_b128 v[202:205], v153 offset:52224
	ds_read_b128 v[206:209], v153 offset:53248
	ds_read_b128 v[210:213], v153 offset:54272
	ds_read_b128 v[214:217], v153 offset:55296
	ds_read_b128 v[218:221], v153 offset:56320
	global_load_lds_dwordx4 v[158:159], off
	s_add_i32 m0, s70, 0x2000
	s_add_u32 s50, s50, 0x40080
	v_lshl_add_u64 v[158:159], v[178:179], 0, s[8:9]
	s_addc_u32 s51, s51, 0
	s_add_i32 s70, s85, s3
	global_load_lds_dwordx4 v[158:159], off
	v_lshl_add_u64 v[158:159], s[50:51], 0, v[132:133]
	s_mov_b32 m0, s70
	s_nop 0
	global_load_lds_dwordx4 v[158:159], off
	v_lshl_add_u64 v[158:159], s[50:51], 0, v[128:129]
	s_add_i32 m0, s70, 0x2000
	s_nop 0
	global_load_lds_dwordx4 v[158:159], off
	v_lshl_add_u64 v[158:159], v[222:223], 0, s[8:9]
	s_mov_b32 m0, s76
	s_nop 0
	global_load_lds_dwordx4 v[158:159], off
	v_lshl_add_u64 v[158:159], v[224:225], 0, s[8:9]
	s_mov_b32 m0, s77
	s_nop 0
	global_load_lds_dwordx4 v[158:159], off
	s_waitcnt vmcnt(8)
	s_waitcnt lgkmcnt(0)
	s_barrier
	s_setprio 1
	s_waitcnt lgkmcnt(0)
	v_mfma_f32_16x16x32_bf16 v[60:63], v[144:147], v[190:193], v[60:63]
	v_mfma_f32_16x16x32_bf16 v[56:59], v[162:165], v[190:193], v[56:59]
	v_mfma_f32_16x16x32_bf16 v[52:55], v[144:147], v[198:201], v[52:55]
	v_mfma_f32_16x16x32_bf16 v[44:47], v[162:165], v[198:201], v[44:47]
	v_mfma_f32_16x16x32_bf16 v[36:39], v[144:147], v[206:209], v[36:39]
	v_mfma_f32_16x16x32_bf16 v[28:31], v[162:165], v[206:209], v[28:31]
	v_mfma_f32_16x16x32_bf16 v[20:23], v[144:147], v[214:217], v[20:23]
	v_mfma_f32_16x16x32_bf16 v[12:15], v[162:165], v[214:217], v[12:15]
	v_mfma_f32_16x16x32_bf16 v[60:63], v[154:157], v[194:197], v[60:63]
	v_mfma_f32_16x16x32_bf16 v[56:59], v[166:169], v[194:197], v[56:59]
	v_mfma_f32_16x16x32_bf16 v[52:55], v[154:157], v[202:205], v[52:55]
	v_mfma_f32_16x16x32_bf16 v[44:47], v[166:169], v[202:205], v[44:47]
	v_mfma_f32_16x16x32_bf16 v[36:39], v[154:157], v[210:213], v[36:39]
	v_mfma_f32_16x16x32_bf16 v[28:31], v[166:169], v[210:213], v[28:31]
	v_mfma_f32_16x16x32_bf16 v[20:23], v[154:157], v[218:221], v[20:23]
	v_mfma_f32_16x16x32_bf16 v[12:15], v[166:169], v[218:221], v[12:15]
	s_setprio 0
	s_setprio 1
	v_mfma_f32_16x16x32_bf16 v[48:51], v[170:173], v[190:193], v[48:51]
	v_mfma_f32_16x16x32_bf16 v[40:43], v[182:185], v[190:193], v[40:43]
	v_mfma_f32_16x16x32_bf16 v[32:35], v[170:173], v[198:201], v[32:35]
	v_mfma_f32_16x16x32_bf16 v[24:27], v[182:185], v[198:201], v[24:27]
	v_mfma_f32_16x16x32_bf16 v[16:19], v[170:173], v[206:209], v[16:19]
	v_mfma_f32_16x16x32_bf16 v[8:11], v[182:185], v[206:209], v[8:11]
	v_mfma_f32_16x16x32_bf16 v[4:7], v[170:173], v[214:217], v[4:7]
	v_mfma_f32_16x16x32_bf16 v[0:3], v[182:185], v[214:217], v[0:3]
	v_mfma_f32_16x16x32_bf16 v[48:51], v[174:177], v[194:197], v[48:51]
	v_mfma_f32_16x16x32_bf16 v[40:43], v[186:189], v[194:197], v[40:43]
	v_mfma_f32_16x16x32_bf16 v[32:35], v[174:177], v[202:205], v[32:35]
	v_mfma_f32_16x16x32_bf16 v[24:27], v[186:189], v[202:205], v[24:27]
	v_mfma_f32_16x16x32_bf16 v[16:19], v[174:177], v[210:213], v[16:19]
	v_mfma_f32_16x16x32_bf16 v[8:11], v[186:189], v[210:213], v[8:11]
	v_mfma_f32_16x16x32_bf16 v[4:7], v[174:177], v[218:221], v[4:7]
	v_mfma_f32_16x16x32_bf16 v[0:3], v[186:189], v[218:221], v[0:3]
	s_setprio 0
	s_barrier
	s_add_i32 s83, s83, 2
	s_add_u32 s40, s40, 0x100
	s_addc_u32 s41, s41, 0
	s_add_u32 s17, s17, 0x100
	s_addc_u32 s19, s19, 0
	s_cmp_gt_u32 s83, 13
	s_cbranch_scc0 .LBB0_75
	s_and_b64 vcc, exec, s[10:11]
	s_cbranch_vccz .LBB0_78
	s_barrier
	s_setprio 1
.LBB0_78:
	v_lshl_add_u32 v156, s24, 8, v148
	v_lshl_or_b32 v146, s82, 8, v150
	v_ashrrev_i32_e32 v147, 31, v146
	v_mov_b64_e32 v[144:145], s[34:35]
	v_cvt_pk_bf16_f32 v68, v68, v69
	v_cvt_pk_bf16_f32 v69, v70, v71
	v_cvt_pk_bf16_f32 v70, v64, v65
	v_add_u32_e32 v64, 0x80, v156
	v_mad_i64_i32 v[154:155], s[40:41], v156, s81, v[144:145]
	v_lshlrev_b64 v[146:147], 1, v[146:147]
	v_cvt_pk_bf16_f32 v112, v112, v113
	v_cvt_pk_bf16_f32 v113, v114, v115
	v_cvt_pk_bf16_f32 v114, v104, v105
	v_or_b32_e32 v104, 16, v156
	v_mad_i64_i32 v[64:65], s[40:41], v64, s81, v[144:145]
	v_cvt_pk_bf16_f32 v48, v48, v49
	v_cvt_pk_bf16_f32 v49, v50, v51
	v_cvt_pk_bf16_f32 v50, v40, v41
	v_add_u32_e32 v40, 0x90, v156
	v_lshl_add_u64 v[154:155], v[154:155], 0, v[146:147]
	v_mad_i64_i32 v[104:105], s[40:41], v104, s81, v[144:145]
	v_cvt_pk_bf16_f32 v96, v96, v97
	v_cvt_pk_bf16_f32 v97, v98, v99
	v_cvt_pk_bf16_f32 v98, v88, v89
	v_or_b32_e32 v88, 32, v156
	v_lshl_add_u64 v[64:65], v[64:65], 0, v[146:147]
	v_mad_i64_i32 v[40:41], s[40:41], v40, s81, v[144:145]
	v_cvt_pk_bf16_f32 v32, v32, v33
	v_cvt_pk_bf16_f32 v33, v34, v35
	v_cvt_pk_bf16_f32 v34, v24, v25
	v_add_u32_e32 v24, 0xa0, v156
	v_cvt_pk_bf16_f32 v115, v106, v107
	global_store_dwordx4 v[154:155], v[112:115], off offset:256 sc1
	v_mad_i64_i32 v[88:89], s[40:41], v88, s81, v[144:145]
	s_nop 0
	v_lshl_add_u64 v[112:113], v[104:105], 0, v[146:147]
	v_cvt_pk_bf16_f32 v80, v80, v81
	v_cvt_pk_bf16_f32 v81, v82, v83
	v_cvt_pk_bf16_f32 v82, v72, v73
	v_or_b32_e32 v72, 48, v156
	v_cvt_pk_bf16_f32 v51, v42, v43
	global_store_dwordx4 v[64:65], v[48:51], off offset:256 sc1
	v_mad_i64_i32 v[24:25], s[40:41], v24, s81, v[144:145]
	s_nop 0
	v_lshl_add_u64 v[48:49], v[40:41], 0, v[146:147]
	v_cvt_pk_bf16_f32 v16, v16, v17
	v_cvt_pk_bf16_f32 v17, v18, v19
	v_cvt_pk_bf16_f32 v18, v8, v9
	v_add_u32_e32 v8, 0xb0, v156
	v_cvt_pk_bf16_f32 v99, v90, v91
	global_store_dwordx4 v[112:113], v[96:99], off offset:256 sc1
	v_mad_i64_i32 v[72:73], s[40:41], v72, s81, v[144:145]
	s_nop 0
	v_lshl_add_u64 v[96:97], v[88:89], 0, v[146:147]
	v_cvt_pk_bf16_f32 v35, v26, v27
	global_store_dwordx4 v[48:49], v[32:35], off offset:256 sc1
	v_mad_i64_i32 v[8:9], s[40:41], v8, s81, v[144:145]
	s_nop 0
	v_lshl_add_u64 v[32:33], v[24:25], 0, v[146:147]
	v_cvt_pk_bf16_f32 v83, v74, v75
	global_store_dwordx4 v[96:97], v[80:83], off offset:256 sc1
	v_cvt_pk_bf16_f32 v19, v10, v11
	global_store_dwordx4 v[32:33], v[16:19], off offset:256 sc1
	s_andn2_b64 vcc, exec, s[4:5]
	v_lshl_add_u64 v[80:81], v[72:73], 0, v[146:147]
	v_lshl_add_u64 v[16:17], v[8:9], 0, v[146:147]
	s_mov_b64 s[4:5], -1
	v_cvt_pk_bf16_f32 v124, v124, v125
	v_cvt_pk_bf16_f32 v125, v126, v127
	v_cvt_pk_bf16_f32 v126, v120, v121
	v_cvt_pk_bf16_f32 v127, v122, v123
	global_store_dwordx4 v[154:155], v[124:127], off sc1
	v_cvt_pk_bf16_f32 v104, v116, v117
	v_cvt_pk_bf16_f32 v105, v118, v119
	v_cvt_pk_bf16_f32 v106, v108, v109
	v_cvt_pk_bf16_f32 v107, v110, v111
	global_store_dwordx4 v[112:113], v[104:107], off sc1
	v_cvt_pk_bf16_f32 v88, v100, v101
	v_cvt_pk_bf16_f32 v89, v102, v103
	v_cvt_pk_bf16_f32 v90, v92, v93
	v_cvt_pk_bf16_f32 v91, v94, v95
	global_store_dwordx4 v[96:97], v[88:91], off sc1
	v_cvt_pk_bf16_f32 v72, v84, v85
	v_cvt_pk_bf16_f32 v73, v86, v87
	v_cvt_pk_bf16_f32 v74, v76, v77
	v_cvt_pk_bf16_f32 v75, v78, v79
	global_store_dwordx4 v[80:81], v[72:75], off sc1
	v_cvt_pk_bf16_f32 v71, v66, v67
	global_store_dwordx4 v[80:81], v[68:71], off offset:256 sc1
	v_cvt_pk_bf16_f32 v60, v60, v61
	v_cvt_pk_bf16_f32 v61, v62, v63
	v_cvt_pk_bf16_f32 v62, v56, v57
	v_cvt_pk_bf16_f32 v63, v58, v59
	global_store_dwordx4 v[64:65], v[60:63], off sc1
	v_cvt_pk_bf16_f32 v40, v52, v53
	v_cvt_pk_bf16_f32 v41, v54, v55
	v_cvt_pk_bf16_f32 v42, v44, v45
	v_cvt_pk_bf16_f32 v43, v46, v47
	global_store_dwordx4 v[48:49], v[40:43], off sc1
	v_cvt_pk_bf16_f32 v24, v36, v37
	v_cvt_pk_bf16_f32 v25, v38, v39
	v_cvt_pk_bf16_f32 v26, v28, v29
	v_cvt_pk_bf16_f32 v27, v30, v31
	global_store_dwordx4 v[32:33], v[24:27], off sc1
	v_cvt_pk_bf16_f32 v8, v20, v21
	v_cvt_pk_bf16_f32 v9, v22, v23
	v_cvt_pk_bf16_f32 v10, v12, v13
	v_cvt_pk_bf16_f32 v11, v14, v15
	global_store_dwordx4 v[16:17], v[8:11], off sc1
	v_cvt_pk_bf16_f32 v4, v4, v5
	v_cvt_pk_bf16_f32 v5, v6, v7
	v_cvt_pk_bf16_f32 v6, v0, v1
	v_cvt_pk_bf16_f32 v7, v2, v3
	global_store_dwordx4 v[16:17], v[4:7], off offset:256 sc1
	s_setprio 0
	s_cbranch_vccnz .LBB0_71
	s_andn2_b64 vcc, exec, s[6:7]
	s_cbranch_vccnz .LBB0_70
	s_barrier
	s_branch .LBB0_70
